# k15b + odd workgroups run the sample-row tile before the main unit in P2/P5/P7 (halves of the chip out of phase)
# baseline (speedup 1.0000x reference)
; #define LAS __attribute__((address_space(3)))
; __device__ __forceinline__ unsigned xb_add(unsigned* p, unsigned v) { return __hip_atomic_fetch_add(p, v, __ATOMIC_RELAXED, __HIP_MEMORY_SCOPE_AGENT); }
; __device__ __forceinline__ unsigned xb_xcc_id() { return (unsigned)__builtin_amdgcn_s_getreg((3 << 11) | 20) & 0xFu; }
; __device__ __forceinline__ XcdBarrier xcd_barrier_post(unsigned* bar, volatile LAS unsigned* st) {
;     XcdBarrier b; b.bar = bar; b.x = xb_xcc_id(); b.st = st;
;     if (threadIdx.x == 0) (void)xb_add(&bar[XB_XCNT(b.x)], 1u);
;     return b;
; }
; __global__ void __launch_bounds__(NWAVES * 64, 2) fwd_megakernel(Args args) {
;     ...
;     F.lds = (LAS unsigned char*)lds_raw; F.tid = threadIdx.x; F.lane = F.tid & 63; F.wave = __builtin_amdgcn_readfirstlane(F.tid >> 6); F.G = gridDim.x;
;     const __attribute__((address_space(4))) Args* KA = (const __attribute__((address_space(4))) Args*)__builtin_amdgcn_kernarg_segment_ptr();
;     F.a = KA; F.out = KA->out;
;     unsigned char* ws = KA->ws;
;     F.Z = (bf16*)(ws + WS_Z); F.MIX = (bf16*)(ws + WS_MIX); F.rope = (const f32x2*)(ws + WS_ROPE);
;     bf16* XG = (bf16*)(ws + WS_XB); bf16* ACT = (bf16*)(ws + WS_ACT); bf16* PRJ = (bf16*)(ws + WS_PRJ); float* SS = (float*)(ws + WS_SS);
;     const int lo = KA->ph_lo, hi = KA->ph_hi;
;     const bool spread = (F.G == 256);
;     ...
;     if (F.tid < 64) ((LAS unsigned*)(F.lds + OFF_MISC))[F.tid] = 0u;
;     __syncthreads();
;     const XcdBarrier bar = xcd_barrier_post((unsigned*)(ws + WS_CTL), (volatile LAS unsigned*)(F.lds + OFF_MISC));
_Z14fwd_megakernel4Args:
	s_mov_b32 s32, 0
	s_load_dwordx8 s[24:31], s[0:1], 0xe8
	s_add_u32 s8, s0, 0x100
	v_and_b32_e32 v192, 0x3ff, v0
	s_addc_u32 s9, s1, 0
	v_readfirstlane_b32 s14, v192
	v_cmp_gt_u32_e32 vcc, 64, v192
	s_and_saveexec_b64 s[4:5], vcc
	v_lshl_add_u32 v1, v192, 2, 0
	v_add_u32_e32 v1, 0x25f00, v1
	v_mov_b32_e32 v2, 0
	ds_write_b32 v1, v2
	s_or_b64 exec, exec, s[4:5]
	s_load_dword s3, s[0:1], 0x108
	s_waitcnt lgkmcnt(0)
	s_add_u32 s4, s26, 0xd490800
	s_addc_u32 s5, s27, 0
	s_barrier
	v_writelane_b32 v254, s3, 0
	v_writelane_b32 v254, s4, 1
	s_getreg_b32 s3, hwreg(HW_REG_XCC_ID, 0, 4)
	s_and_b32 s3, s3, 15
	v_writelane_b32 v254, s5, 2
	v_writelane_b32 v254, s3, 3
	v_cmp_eq_u32_e64 s[4:5], 0, v192
	s_mov_b64 s[6:7], exec
	s_nop 0
	v_writelane_b32 v254, s4, 4
	s_nop 1
	v_writelane_b32 v254, s5, 5
	s_and_b64 s[4:5], s[6:7], s[4:5]
	s_mov_b64 exec, s[4:5]
	s_cbranch_execz .LBB0_5
	s_mov_b64 s[10:11], exec
	v_mbcnt_lo_u32_b32 v1, s10, 0
	v_mbcnt_hi_u32_b32 v1, s11, v1
	v_cmp_eq_u32_e32 vcc, 0, v1
	s_and_b64 s[4:5], exec, vcc
	s_mov_b64 exec, s[4:5]
	s_cbranch_execz .LBB0_5
	v_readlane_b32 s3, v254, 3
	s_bcnt1_i32_b64 s4, s[10:11]
	s_lshl_b32 s3, s3, 8
	v_mov_b32_e32 v2, s4
	v_readlane_b32 s4, v254, 1
	v_mov_b32_e32 v1, s3
	v_readlane_b32 s5, v254, 2
	s_nop 4
	global_atomic_add v1, v2, s[4:5] offset:1024

; __global__ void __launch_bounds__(NWAVES * 64, 2) fwd_megakernel(Args args) {
;     ...
;         pg8::Gemm g{ACT, (const bf16*)(ws + WS_W1D), MP, D, FF}; pg8::StaticOrder S; S.init(MP, D, F.G, (int)blockIdx.x);
;         pg8::EpiRes E{XG, SS, 0.5f};
;         pg8::gemm_phase<pg8::EpiRes, pg8::StaticOrder, true, true>(F.lds, g, S, E);
;         ElemRes Es{XG, SS, 0.5f};
;         gemm_sample_rows<ElemRes>(F, ACT, (const bf16*)(ws + WS_W1D), FF, Es);
.Lsw_p2_main:
	s_cmp_lg_u32 s32, 0
	s_cbranch_scc1 .Lsw_p2_go
	s_bitcmp0_b32 s2, 0
	s_cbranch_scc1 .Lsw_p2_go
	s_mov_b32 s32, 1
	s_add_u32 s14, s26, 0xb00000
	s_addc_u32 s15, s27, 0
	v_mbcnt_lo_u32_b32 v247, -1, 0
	v_mbcnt_hi_u32_b32 v247, -1, v247
	v_and_b32_e32 v56, 64, v247
	v_add_u32_e32 v56, 64, v56
	s_branch .LBB0_391
.Lsw_p2_go:
	v_mov_b32_e32 v12, v192
	s_cmpk_lt_i32 s2, 0x100
	s_movk_i32 s6, 0xb00
	v_readfirstlane_b32 s4, v12
	s_cselect_b64 s[8:9], -1, 0
	s_cmpk_gt_i32 s2, 0xff
	s_cbranch_scc1 .LBB0_350
	s_ashr_i32 s3, s2, 31
	s_lshr_b32 s3, s3, 29
	s_add_i32 s3, s2, s3
	s_and_b32 s5, s3, -8
	s_sub_i32 s5, s2, s5
	s_cmp_gt_i32 s5, -1
	s_cbranch_scc0 .LBB0_347
	s_lshl_b32 s7, s5, 5
	s_cbranch_execz .LBB0_348
	s_branch .LBB0_349

; #define LAS __attribute__((address_space(3)))
;     __device__ __forceinline__ float elem8(int r, int c, f32x4 a0, f32x4 a1) const { float x[8] = {a0[0], a0[1], a0[2], a0[3], a1[0], a1[1], a1[2], a1[3]}; *(v4u*)(P + (size_t)r * D + c) = pack8(x); return 0.f; }
; template <class Elem>
; __device__ __forceinline__ void gemm_small64(LAS unsigned char* lds, const bf16* A, const bf16* Bt, int K, int r0, int c0, const Elem& E) {
;     ...
;     const int row = tid >> 3, c8 = (tid & 7) * 8;
;     f32x4 v0 = {0.f, 0.f, 0.f, 0.f}, v1 = {0.f, 0.f, 0.f, 0.f};
; #pragma unroll
;     for (int ww = 0; ww < 8; ++ww) { v0 += *(const LAS f32x4*)(P + (ww * 64 + row) * 68 + c8); v1 += *(const LAS f32x4*)(P + (ww * 64 + row) * 68 + c8 + 4); }
;     float ss = E.elem8(r0 + row, c0 + c8, v0, v1);
;     if (Elem::HAS_SS) { ss += __shfl_xor(ss, 1); ss += __shfl_xor(ss, 2); ss += __shfl_xor(ss, 4); if ((tid & 7) == 0) E.row_ss(r0 + row, c0 >> 6, ss); }
; template <class Elem>
; __device__ __forceinline__ void gemm_sample_rows(Frame& F, const bf16* A, const bf16* Bt, int K, const Elem& E) {
;     for (int st = blockIdx.x; st < 256; st += F.G) gemm_small64<Elem>(F.lds, A, Bt, K, MP + 64 * (st >> 4), 64 * (st & 15), E);
.LBB0_391:
	s_cmp_eq_u32 s32, 2
	s_cbranch_scc1 .LBB0_395
	v_xor_b32_e32 v0, 1, v247
	v_cmp_lt_i32_e32 vcc, v0, v56
	s_waitcnt vmcnt(0)
	s_lshl_b32 s3, s2, 6
	s_lshl_b32 s4, s30, 6
	v_cndmask_b32_e32 v0, v247, v0, vcc
	v_lshlrev_b32_e32 v42, 2, v0
	v_xor_b32_e32 v0, 2, v247
	v_cmp_lt_i32_e32 vcc, v0, v56
	s_lshl_b32 s5, s2, 2
	s_lshl_b32 s10, s30, 2
	v_cndmask_b32_e32 v0, v247, v0, vcc
	v_lshlrev_b32_e32 v43, 2, v0
	v_xor_b32_e32 v0, 4, v247
	v_cmp_lt_i32_e32 vcc, v0, v56
	s_movk_i32 s11, 0x1600
	v_mov_b64_e32 v[28:29], s[52:53]
	v_cndmask_b32_e32 v0, v247, v0, vcc
	v_lshlrev_b32_e32 v44, 2, v0
	v_mov_b32_e32 v31, 0
	s_mov_b32 s16, 0x16000
	s_mov_b32 s7, 0
	s_mov_b32 s17, 0x2c000
	s_mov_b32 s18, 0x42000
	s_movk_i32 s19, 0x110
	s_mov_b32 s20, s2
	s_barrier
	s_branch .LBB0_393

; #define SEAM(k) do { if (IN(k) && IN((k) + 1)) xcd_barrier(bar); } while (0)
; __device__ __forceinline__ void xcd_barrier(const XcdBarrier& b) {
;     asm volatile("s_waitcnt vmcnt(0)" ::: "memory");
;     __syncthreads();
;     if (threadIdx.x == 0) {
;         unsigned* bar = b.bar;
;         __builtin_amdgcn_s_waitcnt(0);
;         unsigned nloc = b.st[0], nx = b.st[1];
;         if (nloc == 0u) { xcd_barrier_complete(bar, b.x, nloc, nx); b.st[0] = nloc; b.st[1] = nx; }
; __global__ void __launch_bounds__(NWAVES * 64, 2) fwd_megakernel(Args args) {
;     ...
;         gemm_sample_rows<ElemRes>(F, ACT, (const bf16*)(ws + WS_W1D), FF, Es);
;     } SEAM(2);
.LBB0_395:
	s_cmp_lg_u32 s32, 1
	s_cbranch_scc1 .Lsw_p2_done
	s_mov_b32 s32, 2
	s_branch .Lsw_p2_main
.Lsw_p2_done:
	s_mov_b32 s32, 0
	s_cmp_gt_i32 s29, 3
	s_cselect_b64 s[6:7], -1, 0
	s_and_b64 s[4:5], s[12:13], s[6:7]
	s_andn2_b64 vcc, exec, s[4:5]
	s_cbranch_vccnz .LBB0_447
	s_waitcnt vmcnt(0)
	s_waitcnt vmcnt(0) lgkmcnt(0)
	s_barrier
	s_mov_b64 s[8:9], exec
	v_readlane_b32 s4, v254, 4
	v_readlane_b32 s5, v254, 5
	s_and_b64 s[4:5], s[8:9], s[4:5]
	s_mov_b64 exec, s[4:5]
	s_cbranch_execz .LBB0_446
	s_add_i32 s3, 0, 0x25f00
	v_mov_b32_e32 v0, s3
	s_waitcnt vmcnt(0) expcnt(0) lgkmcnt(0)
	ds_read_b32 v2, v0
	s_add_i32 s3, 0, 0x25f04
	v_mov_b32_e32 v0, s3
	ds_read_b32 v0, v0
	s_waitcnt lgkmcnt(1)
	v_cmp_ne_u32_e32 vcc, 0, v2
	s_cbranch_vccnz .LBB0_412
	s_add_u32 s10, s26, 0xd490a00
	s_addc_u32 s11, s27, 0
	s_add_u32 s12, s26, 0xd490c00
	s_addc_u32 s13, s27, 0
	s_add_u32 s14, s26, 0xd490d00
	s_addc_u32 s15, s27, 0
	s_add_u32 s16, s26, 0xd490e00
	s_addc_u32 s17, s27, 0
	s_add_u32 s18, s26, 0xd490f00
	s_addc_u32 s19, s27, 0
	s_add_u32 s20, s26, 0xd491000
	s_addc_u32 s21, s27, 0
	s_add_u32 s22, s26, 0xd491100
	s_addc_u32 s23, s27, 0
	s_add_u32 s36, s26, 0xd491200
	s_addc_u32 s37, s27, 0
	s_add_u32 s40, s26, 0xd491300
	s_addc_u32 s41, s27, 0
	s_add_u32 s42, s26, 0xd491400
	s_addc_u32 s43, s27, 0
	s_add_u32 s56, s26, 0xd491500
	s_addc_u32 s57, s27, 0
	s_add_u32 s58, s26, 0xd491600
	s_addc_u32 s59, s27, 0
	s_add_u32 s60, s26, 0xd491700
	s_addc_u32 s61, s27, 0
	s_add_u32 s62, s26, 0xd491800
	s_load_dword s3, s[0:1], 0x108
	s_addc_u32 s63, s27, 0
	s_add_u32 s64, s26, 0xd491900
	s_addc_u32 s65, s27, 0
	s_add_u32 s66, s26, 0xd491a00
	s_addc_u32 s67, s27, 0
	s_waitcnt lgkmcnt(0)
	s_mul_i32 s3, s31, s3
	s_add_u32 s68, s26, 0xd491b00
	s_mul_i32 s3, s3, s30
	s_addc_u32 s69, s27, 0
	s_mov_b32 s4, 1
	v_mov_b32_e32 v16, 0
	s_branch .LBB0_400

; __global__ void __launch_bounds__(NWAVES * 64, 2) fwd_megakernel(Args args) {
;     ...
;         pg8::Gemm g{F.MIX, (const bf16*)(ws + WS_WO), MP, D, D}; pg8::StaticOrder S; S.init(MP, D, F.G, (int)blockIdx.x);
;         pg8::EpiRes E{XG, SS, 1.0f};
;         pg8::gemm_phase<pg8::EpiRes, pg8::StaticOrder, true, true>(F.lds, g, S, E);
;         ElemRes Es{XG, SS, 1.0f};
;         gemm_sample_rows<ElemRes>(F, F.MIX, (const bf16*)(ws + WS_WO), D, Es);
.Lsw_p5_main:
	s_cmp_lg_u32 s32, 0
	s_cbranch_scc1 .Lsw_p5_go
	s_bitcmp0_b32 s2, 0
	s_cbranch_scc1 .Lsw_p5_go
	s_mov_b32 s32, 1
	s_add_u32 s12, s26, 0x1400000
	s_addc_u32 s13, s27, 0
	v_mbcnt_lo_u32_b32 v246, -1, 0
	v_mbcnt_hi_u32_b32 v246, -1, v246
	v_and_b32_e32 v112, 64, v246
	v_add_u32_e32 v112, 64, v112
	s_branch .LBB0_943
.Lsw_p5_go:
	v_mov_b32_e32 v12, v192
	s_cmpk_lt_i32 s2, 0x100
	s_movk_i32 s0, 0x400
	v_readfirstlane_b32 s5, v12
	s_cselect_b64 s[6:7], -1, 0
	s_cmpk_gt_i32 s2, 0xff
	s_cbranch_scc1 .LBB0_903
	s_ashr_i32 s1, s2, 31
	s_lshr_b32 s1, s1, 29
	s_add_i32 s1, s2, s1
	s_and_b32 s3, s1, -8
	s_sub_i32 s3, s2, s3
	s_cmp_gt_i32 s3, -1
	s_cbranch_scc0 .LBB0_900
	s_lshl_b32 s4, s3, 5
	s_cbranch_execz .LBB0_901
	s_branch .LBB0_902

; #define LAS __attribute__((address_space(3)))
;     __device__ __forceinline__ float elem8(int r, int c, f32x4 a0, f32x4 a1) const { float x[8] = {a0[0], a0[1], a0[2], a0[3], a1[0], a1[1], a1[2], a1[3]}; *(v4u*)(P + (size_t)r * D + c) = pack8(x); return 0.f; }
; template <class Elem>
; __device__ __forceinline__ void gemm_small64(LAS unsigned char* lds, const bf16* A, const bf16* Bt, int K, int r0, int c0, const Elem& E) {
;     ...
;     const int row = tid >> 3, c8 = (tid & 7) * 8;
;     f32x4 v0 = {0.f, 0.f, 0.f, 0.f}, v1 = {0.f, 0.f, 0.f, 0.f};
; #pragma unroll
;     for (int ww = 0; ww < 8; ++ww) { v0 += *(const LAS f32x4*)(P + (ww * 64 + row) * 68 + c8); v1 += *(const LAS f32x4*)(P + (ww * 64 + row) * 68 + c8 + 4); }
;     float ss = E.elem8(r0 + row, c0 + c8, v0, v1);
;     if (Elem::HAS_SS) { ss += __shfl_xor(ss, 1); ss += __shfl_xor(ss, 2); ss += __shfl_xor(ss, 4); if ((tid & 7) == 0) E.row_ss(r0 + row, c0 >> 6, ss); }
; template <class Elem>
; __device__ __forceinline__ void gemm_sample_rows(Frame& F, const bf16* A, const bf16* Bt, int K, const Elem& E) {
;     for (int st = blockIdx.x; st < 256; st += F.G) gemm_small64<Elem>(F.lds, A, Bt, K, MP + 64 * (st >> 4), 64 * (st & 15), E);
.LBB0_943:
	s_cmp_eq_u32 s32, 2
	s_cbranch_scc1 .LBB0_947
	v_xor_b32_e32 v0, 1, v246
	v_cmp_lt_i32_e32 vcc, v0, v112
	s_waitcnt vmcnt(0)
	s_lshl_b32 s3, s2, 6
	s_lshl_b32 s4, s30, 6
	v_cndmask_b32_e32 v0, v246, v0, vcc
	v_lshlrev_b32_e32 v4, 2, v0
	v_xor_b32_e32 v0, 2, v246
	v_cmp_lt_i32_e32 vcc, v0, v112
	s_lshl_b32 s5, s2, 2
	s_lshl_b32 s8, s30, 2
	v_cndmask_b32_e32 v0, v246, v0, vcc
	v_lshlrev_b32_e32 v5, 2, v0
	v_xor_b32_e32 v0, 4, v246
	v_cmp_lt_i32_e32 vcc, v0, v112
	s_waitcnt lgkmcnt(0)
	v_mov_b32_e32 v1, 0
	s_mov_b32 s9, 0x8000
	v_cndmask_b32_e32 v0, v246, v0, vcc
	v_lshlrev_b32_e32 v6, 2, v0
	s_mov_b32 s1, 0
	s_mov_b32 s14, 0x10000
	s_mov_b32 s15, 0x18000
	s_movk_i32 s16, 0x110
	s_mov_b32 s17, s2
	s_barrier
	s_branch .LBB0_945

; #define SEAM(k) do { if (IN(k) && IN((k) + 1)) xcd_barrier(bar); } while (0)
; __device__ __forceinline__ void xcd_barrier(const XcdBarrier& b) {
;     asm volatile("s_waitcnt vmcnt(0)" ::: "memory");
;     __syncthreads();
;     if (threadIdx.x == 0) {
;         unsigned* bar = b.bar;
;         __builtin_amdgcn_s_waitcnt(0);
;         unsigned nloc = b.st[0], nx = b.st[1];
;         if (nloc == 0u) { xcd_barrier_complete(bar, b.x, nloc, nx); b.st[0] = nloc; b.st[1] = nx; }
; __global__ void __launch_bounds__(NWAVES * 64, 2) fwd_megakernel(Args args) {
;     ...
;     } SEAM(5);
.Lsw_p5_done:
	s_mov_b32 s32, 0
	s_cmp_gt_i32 s29, 6
	s_cselect_b64 s[0:1], -1, 0
	s_and_b64 s[4:5], s[10:11], s[0:1]
	s_andn2_b64 vcc, exec, s[4:5]
	s_cbranch_vccnz .LBB0_999
	s_waitcnt vmcnt(0)
	s_waitcnt vmcnt(0) lgkmcnt(0)
	s_barrier
	s_mov_b64 s[6:7], exec
	v_readlane_b32 s4, v254, 4
	v_readlane_b32 s5, v254, 5
	s_and_b64 s[4:5], s[6:7], s[4:5]
	s_mov_b64 exec, s[4:5]
	s_cbranch_execz .LBB0_998
	s_add_i32 s3, 0, 0x25f00
	v_mov_b32_e32 v0, s3
	s_waitcnt vmcnt(0) expcnt(0) lgkmcnt(0)
	ds_read_b32 v2, v0
	s_add_i32 s3, 0, 0x25f04
	v_mov_b32_e32 v0, s3
	ds_read_b32 v0, v0
	s_waitcnt lgkmcnt(1)
	v_cmp_ne_u32_e32 vcc, 0, v2
	s_cbranch_vccnz .LBB0_964
	s_add_u32 s8, s26, 0xd490a00
	s_addc_u32 s9, s27, 0
	s_add_u32 s10, s26, 0xd490c00
	s_addc_u32 s11, s27, 0
	s_add_u32 s12, s26, 0xd490d00
	s_addc_u32 s13, s27, 0
	s_add_u32 s14, s26, 0xd490e00
	s_addc_u32 s15, s27, 0
	s_add_u32 s16, s26, 0xd490f00
	s_addc_u32 s17, s27, 0
	s_add_u32 s18, s26, 0xd491000
	s_addc_u32 s19, s27, 0
	s_add_u32 s20, s26, 0xd491100
	s_addc_u32 s21, s27, 0
	s_add_u32 s22, s26, 0xd491200
	s_addc_u32 s23, s27, 0
	s_add_u32 s36, s26, 0xd491300
	s_addc_u32 s37, s27, 0
	s_add_u32 s38, s26, 0xd491400
	s_addc_u32 s39, s27, 0
	s_add_u32 s40, s26, 0xd491500
	s_addc_u32 s41, s27, 0
	s_add_u32 s42, s26, 0xd491600
	s_addc_u32 s43, s27, 0
	s_add_u32 s56, s26, 0xd491700
	s_addc_u32 s57, s27, 0
	s_add_u32 s58, s26, 0xd491800
	s_addc_u32 s59, s27, 0
	s_add_u32 s60, s26, 0xd491900
	s_addc_u32 s61, s27, 0
	s_add_u32 s62, s26, 0xd491a00
	v_readlane_b32 s3, v254, 0
	s_addc_u32 s63, s27, 0
	s_mul_i32 s3, s31, s3
	s_add_u32 s64, s26, 0xd491b00
	s_mul_i32 s3, s3, s30
	s_addc_u32 s65, s27, 0
	s_mov_b32 s4, 1
	v_mov_b32_e32 v16, 0
	s_branch .LBB0_952

; __global__ void __launch_bounds__(NWAVES * 64, 2) fwd_megakernel(Args args) {
;     ...
;         pg8::Gemm g{ACT, (const bf16*)(ws + WS_W2D), MP, D, FF}; pg8::StaticOrder S; S.init(MP, D, F.G, (int)blockIdx.x);
;         pg8::EpiRes E{XG, SS, 0.5f};
;         pg8::gemm_phase<pg8::EpiRes, pg8::StaticOrder, true, true>(F.lds, g, S, E);
;         ElemRes Es{XG, SS, 0.5f};
;         gemm_sample_rows<ElemRes>(F, ACT, (const bf16*)(ws + WS_W2D), FF, Es);
.Lsw_p7_main:
	s_cmp_lg_u32 s32, 0
	s_cbranch_scc1 .Lsw_p7_go
	s_bitcmp0_b32 s2, 0
	s_cbranch_scc1 .Lsw_p7_go
	s_mov_b32 s32, 1
	s_add_u32 s12, s26, 0x2100000
	s_addc_u32 s13, s27, 0
	v_mbcnt_lo_u32_b32 v246, -1, 0
	v_mbcnt_hi_u32_b32 v246, -1, v246
	v_and_b32_e32 v56, 64, v246
	v_add_u32_e32 v56, 64, v56
	s_branch .LBB0_1141
.Lsw_p7_go:
	v_mov_b32_e32 v12, v192
	s_cmpk_lt_i32 s2, 0x100
	s_movk_i32 s0, 0xb00
	v_readfirstlane_b32 s4, v12
	s_cselect_b64 s[6:7], -1, 0
	s_cmpk_gt_i32 s2, 0xff
	s_cbranch_scc1 .LBB0_1100
	s_ashr_i32 s1, s2, 31
	s_lshr_b32 s1, s1, 29
	s_add_i32 s1, s2, s1
	s_and_b32 s3, s1, -8
	s_sub_i32 s3, s2, s3
	s_cmp_gt_i32 s3, -1
	s_cbranch_scc0 .LBB0_1097
	s_lshl_b32 s5, s3, 5
	s_cbranch_execz .LBB0_1098
	s_branch .LBB0_1099

; #define LAS __attribute__((address_space(3)))
;     __device__ __forceinline__ float elem8(int r, int c, f32x4 a0, f32x4 a1) const { float x[8] = {a0[0], a0[1], a0[2], a0[3], a1[0], a1[1], a1[2], a1[3]}; *(v4u*)(P + (size_t)r * D + c) = pack8(x); return 0.f; }
; template <class Elem>
; __device__ __forceinline__ void gemm_small64(LAS unsigned char* lds, const bf16* A, const bf16* Bt, int K, int r0, int c0, const Elem& E) {
;     ...
;     const int row = tid >> 3, c8 = (tid & 7) * 8;
;     f32x4 v0 = {0.f, 0.f, 0.f, 0.f}, v1 = {0.f, 0.f, 0.f, 0.f};
; #pragma unroll
;     for (int ww = 0; ww < 8; ++ww) { v0 += *(const LAS f32x4*)(P + (ww * 64 + row) * 68 + c8); v1 += *(const LAS f32x4*)(P + (ww * 64 + row) * 68 + c8 + 4); }
;     float ss = E.elem8(r0 + row, c0 + c8, v0, v1);
;     if (Elem::HAS_SS) { ss += __shfl_xor(ss, 1); ss += __shfl_xor(ss, 2); ss += __shfl_xor(ss, 4); if ((tid & 7) == 0) E.row_ss(r0 + row, c0 >> 6, ss); }
; template <class Elem>
; __device__ __forceinline__ void gemm_sample_rows(Frame& F, const bf16* A, const bf16* Bt, int K, const Elem& E) {
;     for (int st = blockIdx.x; st < 256; st += F.G) gemm_small64<Elem>(F.lds, A, Bt, K, MP + 64 * (st >> 4), 64 * (st & 15), E);
.LBB0_1141:
	s_cmp_eq_u32 s32, 2
	s_cbranch_scc1 .LBB0_1145
	v_xor_b32_e32 v0, 1, v246
	v_cmp_lt_i32_e32 vcc, v0, v56
	s_waitcnt vmcnt(0)
	s_lshl_b32 s3, s2, 6
	s_lshl_b32 s4, s30, 6
	v_cndmask_b32_e32 v0, v246, v0, vcc
	v_lshlrev_b32_e32 v42, 2, v0
	v_xor_b32_e32 v0, 2, v246
	v_cmp_lt_i32_e32 vcc, v0, v56
	s_lshl_b32 s5, s2, 2
	s_lshl_b32 s8, s30, 2
	v_cndmask_b32_e32 v0, v246, v0, vcc
	v_lshlrev_b32_e32 v43, 2, v0
	v_xor_b32_e32 v0, 4, v246
	v_cmp_lt_i32_e32 vcc, v0, v56
	s_movk_i32 s9, 0x1600
	v_mov_b64_e32 v[28:29], s[52:53]
	v_cndmask_b32_e32 v0, v246, v0, vcc
	v_lshlrev_b32_e32 v44, 2, v0
	v_mov_b32_e32 v31, 0
	s_mov_b32 s14, 0x16000
	s_mov_b32 s1, 0
	s_mov_b32 s15, 0x2c000
	s_mov_b32 s16, 0x42000
	s_movk_i32 s17, 0x110
	s_mov_b32 s18, s2
	s_barrier
	s_branch .LBB0_1143

; #define SEAM(k) do { if (IN(k) && IN((k) + 1)) xcd_barrier(bar); } while (0)
; __device__ __forceinline__ void xcd_barrier(const XcdBarrier& b) {
;     asm volatile("s_waitcnt vmcnt(0)" ::: "memory");
;     __syncthreads();
;     if (threadIdx.x == 0) {
;         unsigned* bar = b.bar;
;         __builtin_amdgcn_s_waitcnt(0);
;         unsigned nloc = b.st[0], nx = b.st[1];
;         if (nloc == 0u) { xcd_barrier_complete(bar, b.x, nloc, nx); b.st[0] = nloc; b.st[1] = nx; }
; __global__ void __launch_bounds__(NWAVES * 64, 2) fwd_megakernel(Args args) {
;     ...
;     } SEAM(7);
.Lsw_p7_done:
	s_mov_b32 s32, 0
	s_cmp_gt_i32 s29, 8
	s_cselect_b64 s[0:1], -1, 0
	s_and_b64 s[4:5], s[10:11], s[0:1]
	s_andn2_b64 vcc, exec, s[4:5]
	s_cbranch_vccnz .LBB0_1197
	s_waitcnt vmcnt(0)
	s_waitcnt vmcnt(0) lgkmcnt(0)
	s_barrier
	s_mov_b64 s[6:7], exec
	v_readlane_b32 s4, v254, 4
	v_readlane_b32 s5, v254, 5
	s_and_b64 s[4:5], s[6:7], s[4:5]
	s_mov_b64 exec, s[4:5]
	s_cbranch_execz .LBB0_1196
	s_add_i32 s3, 0, 0x25f00
	v_mov_b32_e32 v0, s3
	s_waitcnt vmcnt(0) expcnt(0) lgkmcnt(0)
	ds_read_b32 v2, v0
	s_add_i32 s3, 0, 0x25f04
	v_mov_b32_e32 v0, s3
	ds_read_b32 v0, v0
	s_waitcnt lgkmcnt(1)
	v_cmp_ne_u32_e32 vcc, 0, v2
	s_cbranch_vccnz .LBB0_1162
	s_add_u32 s4, s26, 0xd490a00
	s_addc_u32 s5, s27, 0
	s_add_u32 s8, s26, 0xd490c00
	s_addc_u32 s9, s27, 0
	s_add_u32 s10, s26, 0xd490d00
	s_addc_u32 s11, s27, 0
	s_add_u32 s12, s26, 0xd490e00
	s_addc_u32 s13, s27, 0
	s_add_u32 s14, s26, 0xd490f00
	s_addc_u32 s15, s27, 0
	s_add_u32 s16, s26, 0xd491000
	s_addc_u32 s17, s27, 0
	s_add_u32 s18, s26, 0xd491100
	s_addc_u32 s19, s27, 0
	s_add_u32 s20, s26, 0xd491200
	s_addc_u32 s21, s27, 0
	s_add_u32 s22, s26, 0xd491300
	s_addc_u32 s23, s27, 0
	s_add_u32 s36, s26, 0xd491400
	s_addc_u32 s37, s27, 0
	s_add_u32 s38, s26, 0xd491500
	s_addc_u32 s39, s27, 0
	s_add_u32 s40, s26, 0xd491600
	s_addc_u32 s41, s27, 0
	s_add_u32 s42, s26, 0xd491700
	s_addc_u32 s43, s27, 0
	s_add_u32 s52, s26, 0xd491800
	s_addc_u32 s53, s27, 0
	s_add_u32 s54, s26, 0xd491900
	s_addc_u32 s55, s27, 0
	s_add_u32 s56, s26, 0xd491a00
	v_readlane_b32 s3, v254, 0
	s_addc_u32 s57, s27, 0
	s_mul_i32 s3, s31, s3
	s_add_u32 s58, s26, 0xd491b00
	s_mul_i32 s3, s3, s30
	s_addc_u32 s59, s27, 0
	s_mov_b32 s29, 1
	v_mov_b32_e32 v16, 0
	s_branch .LBB0_1150
